# grid barrier: non-leader workgroups poll the top-level generation word directly (XGEN hop removed), leaders skip the XGEN add
# speedup vs baseline: 1.0089x; 1.0089x over previous
; __device__ __forceinline__ unsigned xb_ld(unsigned* p)              { return __hip_atomic_load(p, __ATOMIC_RELAXED, __HIP_MEMORY_SCOPE_AGENT); }
; __device__ __forceinline__ unsigned xb_add(unsigned* p, unsigned v) { return __hip_atomic_fetch_add(p, v, __ATOMIC_RELAXED, __HIP_MEMORY_SCOPE_AGENT); }
; #define XB_SPIN(cond, bar) do { unsigned _sp = 0; while (cond) { __builtin_amdgcn_s_sleep(1); \
;     if ((++_sp & 255u) == 0u) { if (xb_ld(&(bar)[XB_TMO])) break; if (_sp > XB_SPIN_CAP) { atomicAdd(&(bar)[XB_TMO], 1u); break; } } } } while (0)
; __device__ __forceinline__ void xcd_barrier(unsigned* bar, unsigned x, volatile LAS unsigned* st) {
;     ...
;         const unsigned old = xb_add(&bar[XB_XSUB(x)], 1u);
;         const unsigned gen = old / nloc;
;         if (old + 1u == (gen + 1u) * nloc) {
;             __builtin_amdgcn_fence(__ATOMIC_RELEASE, "agent");
;             asm volatile("s_waitcnt vmcnt(0)" ::: "memory");
;             const unsigned og = xb_add(&bar[XB_TOP], 1u);
;             const unsigned tg = og / nx;
;             if (og + 1u == (tg + 1u) * nx) xb_add(&bar[XB_TOPGEN], 1u);
;             else XB_SPIN(xb_ld(&bar[XB_TOPGEN]) == tg, bar);
;             __builtin_amdgcn_fence(__ATOMIC_ACQUIRE, "agent");
;             xb_add(&bar[XB_XGEN(x)], 1u);
;             asm volatile("s_waitcnt vmcnt(0)" ::: "memory");
;         } else {
;             XB_SPIN(xb_ld(&bar[XB_XGEN(x)]) == gen, bar);
.LBB0_864:
	s_or_b64 exec, exec, s[8:9]
	v_cvt_f32_u32_e32 v4, v2
	s_waitcnt vmcnt(0)
	v_readfirstlane_b32 s2, v3
	v_sub_u32_e32 v3, 0, v2
	v_rcp_iflag_f32_e32 v4, v4
	v_add_u32_e32 v5, s2, v1
	v_mul_f32_e32 v4, 0x4f7ffffe, v4
	v_cvt_u32_f32_e32 v4, v4
	v_mul_lo_u32 v1, v3, v4
	v_mul_hi_u32 v1, v4, v1
	v_add_u32_e32 v1, v4, v1
	v_mul_hi_u32 v1, v5, v1
	v_mul_lo_u32 v3, v1, v2
	v_sub_u32_e32 v3, v5, v3
	v_add_u32_e32 v4, 1, v1
	v_cmp_ge_u32_e32 vcc, v3, v2
	s_nop 1
	v_cndmask_b32_e32 v1, v1, v4, vcc
	v_sub_u32_e32 v4, v3, v2
	v_cndmask_b32_e32 v3, v3, v4, vcc
	v_add_u32_e32 v4, 1, v1
	v_cmp_ge_u32_e32 vcc, v3, v2
	v_add_u32_e32 v3, 1, v5
	s_nop 0
	v_cndmask_b32_e32 v1, v1, v4, vcc
	v_mul_lo_u32 v4, v2, v1
	v_add_u32_e32 v2, v4, v2
	v_cmp_ne_u32_e32 vcc, v3, v2
	s_and_saveexec_b64 s[2:3], vcc
	s_xor_b64 s[6:7], exec, s[2:3]
	s_cbranch_execz .LBB0_878
	v_readlane_b32 s10, v254, 32
	v_readlane_b32 s11, v254, 33
	s_waitcnt lgkmcnt(0)
	s_nop 3
	global_load_dword v0, v33, s[10:11] sc1
	s_waitcnt vmcnt(0)
	v_cmp_eq_u32_e32 vcc, v0, v1
	s_and_saveexec_b64 s[8:9], vcc
	s_cbranch_execz .LBB0_877
	s_mov_b32 s2, 0x40000
	global_load_dword v0, v33, s[10:11] sc1

; __device__ __forceinline__ unsigned xb_ld(unsigned* p)              { return __hip_atomic_load(p, __ATOMIC_RELAXED, __HIP_MEMORY_SCOPE_AGENT); }
; __device__ __forceinline__ unsigned xb_add(unsigned* p, unsigned v) { return __hip_atomic_fetch_add(p, v, __ATOMIC_RELAXED, __HIP_MEMORY_SCOPE_AGENT); }
; #define XB_SPIN(cond, bar) do { unsigned _sp = 0; while (cond) { __builtin_amdgcn_s_sleep(1); \
;     if ((++_sp & 255u) == 0u) { if (xb_ld(&(bar)[XB_TMO])) break; if (_sp > XB_SPIN_CAP) { atomicAdd(&(bar)[XB_TMO], 1u); break; } } } } while (0)
; __device__ __forceinline__ void xcd_barrier(unsigned* bar, unsigned x, volatile LAS unsigned* st) {
;     ...
;             if (og + 1u == (tg + 1u) * nx) xb_add(&bar[XB_TOPGEN], 1u);
;             else XB_SPIN(xb_ld(&bar[XB_TOPGEN]) == tg, bar);
;             __builtin_amdgcn_fence(__ATOMIC_ACQUIRE, "agent");
;             xb_add(&bar[XB_XGEN(x)], 1u);
;             asm volatile("s_waitcnt vmcnt(0)" ::: "memory");
.LBB0_897:
	s_waitcnt vmcnt(0)
	buffer_inv sc1
	s_waitcnt vmcnt(0)
